# prologue row pass: all 8 rows of a wave loaded up front instead of one row in flight
# baseline (speedup 1.0000x reference)
.LBB0_671:
	s_or_b64 exec, exec, s[4:5]
	s_cmpk_gt_i32 s8, 0x3fff
	s_cbranch_scc1 .LBB0_676
	s_ashr_i32 s9, s8, 31
	s_lshl_b64 s[4:5], s[8:9], 11
	s_add_u32 s4, s80, s4
	s_addc_u32 s5, s81, s5
	s_ashr_i32 s7, s6, 31
	s_lshl_b64 s[10:11], s[6:7], 11
	s_lshl_b64 s[12:13], s[8:9], 2
	s_add_u32 s12, s78, s12
	s_addc_u32 s13, s79, s13
	s_lshl_b64 s[14:15], s[6:7], 2
	s_lshl_b64 s[16:17], s[8:9], 12
	v_readlane_b32 s56, v254, 14
	v_lshlrev_b32_e32 v2, 2, v218
	v_readlane_b32 s57, v254, 15
	s_add_u32 s16, s56, s16
	v_xor_b32_e32 v1, 4, v2
	v_xor_b32_e32 v20, 8, v2
	v_xor_b32_e32 v21, 16, v2
	v_xor_b32_e32 v22, 32, v2
	v_xor_b32_e32 v23, 64, v2
	v_xor_b32_e32 v24, 0x80, v2
	v_lshlrev_b32_e32 v2, 4, v218
	s_waitcnt lgkmcnt(0)
	v_mov_b32_e32 v3, v0
	s_addc_u32 s17, s57, s17
	v_lshl_add_u64 v[2:3], s[16:17], 0, v[2:3]
	s_mov_b64 s[16:17], 0xc00
	v_cmp_eq_u32_e32 vcc, 0, v218
	v_lshl_add_u64 v[18:19], v[2:3], 0, s[16:17]
	s_lshl_b64 s[16:17], s[6:7], 12
	v_lshlrev_b32_e32 v25, 3, v218
	s_mov_b32 s7, s8
	v_readlane_b32 s58, v254, 16
	v_readlane_b32 s59, v254, 17
	v_readlane_b32 s60, v254, 18
	v_readlane_b32 s61, v254, 19
	v_readlane_b32 s62, v254, 20
	v_readlane_b32 s63, v254, 21
	v_readlane_b32 s64, v254, 22
	v_readlane_b32 s65, v254, 23
	v_readlane_b32 s66, v254, 24
	v_readlane_b32 s67, v254, 25
	v_readlane_b32 s68, v254, 26
	v_readlane_b32 s69, v254, 27
	v_readlane_b32 s70, v254, 28
	v_readlane_b32 s71, v254, 29
	s_cmpk_lg_i32 s6, 0x800
	s_cbranch_scc1 .LBB0_674
	global_load_dwordx4 v[46:49], v[18:19], off offset:-3072 nt
	global_load_dwordx4 v[42:45], v[18:19], off offset:-2048 nt
	global_load_dwordx4 v[38:41], v[18:19], off offset:-1024 nt
	global_load_dwordx4 v[34:37], v[18:19], off nt
	v_lshl_add_u64 v[18:19], v[18:19], 0, s[16:17]
	global_load_dwordx4 v[62:65], v[18:19], off offset:-3072 nt
	global_load_dwordx4 v[58:61], v[18:19], off offset:-2048 nt
	global_load_dwordx4 v[54:57], v[18:19], off offset:-1024 nt
	global_load_dwordx4 v[50:53], v[18:19], off nt
	v_lshl_add_u64 v[18:19], v[18:19], 0, s[16:17]
	global_load_dwordx4 v[78:81], v[18:19], off offset:-3072 nt
	global_load_dwordx4 v[74:77], v[18:19], off offset:-2048 nt
	global_load_dwordx4 v[70:73], v[18:19], off offset:-1024 nt
	global_load_dwordx4 v[66:69], v[18:19], off nt
	v_lshl_add_u64 v[18:19], v[18:19], 0, s[16:17]
	global_load_dwordx4 v[94:97], v[18:19], off offset:-3072 nt
	global_load_dwordx4 v[90:93], v[18:19], off offset:-2048 nt
	global_load_dwordx4 v[86:89], v[18:19], off offset:-1024 nt
	global_load_dwordx4 v[82:85], v[18:19], off nt
	v_lshl_add_u64 v[18:19], v[18:19], 0, s[16:17]
	global_load_dwordx4 v[110:113], v[18:19], off offset:-3072 nt
	global_load_dwordx4 v[106:109], v[18:19], off offset:-2048 nt
	global_load_dwordx4 v[102:105], v[18:19], off offset:-1024 nt
	global_load_dwordx4 v[98:101], v[18:19], off nt
	v_lshl_add_u64 v[18:19], v[18:19], 0, s[16:17]
	global_load_dwordx4 v[126:129], v[18:19], off offset:-3072 nt
	global_load_dwordx4 v[122:125], v[18:19], off offset:-2048 nt
	global_load_dwordx4 v[118:121], v[18:19], off offset:-1024 nt
	global_load_dwordx4 v[114:117], v[18:19], off nt
	v_lshl_add_u64 v[18:19], v[18:19], 0, s[16:17]
	global_load_dwordx4 v[142:145], v[18:19], off offset:-3072 nt
	global_load_dwordx4 v[138:141], v[18:19], off offset:-2048 nt
	global_load_dwordx4 v[134:137], v[18:19], off offset:-1024 nt
	global_load_dwordx4 v[130:133], v[18:19], off nt
	v_lshl_add_u64 v[18:19], v[18:19], 0, s[16:17]
	global_load_dwordx4 v[158:161], v[18:19], off offset:-3072 nt
	global_load_dwordx4 v[154:157], v[18:19], off offset:-2048 nt
	global_load_dwordx4 v[150:153], v[18:19], off offset:-1024 nt
	global_load_dwordx4 v[146:149], v[18:19], off nt
	s_waitcnt vmcnt(28)
	v_mul_f32_e32 v26, v47, v47
	v_mul_f32_e32 v27, v49, v49
	v_mul_f32_e32 v28, v43, v43
	v_mul_f32_e32 v29, v45, v45
	v_mul_f32_e32 v30, v39, v39
	v_mul_f32_e32 v31, v41, v41
	v_fmac_f32_e32 v26, v46, v46
	v_fmac_f32_e32 v27, v48, v48
	v_fmac_f32_e32 v28, v42, v42
	v_fmac_f32_e32 v29, v44, v44
	v_mul_f32_e32 v32, v35, v35
	v_mul_f32_e32 v33, v37, v37
	v_fmac_f32_e32 v30, v38, v38
	v_fmac_f32_e32 v31, v40, v40
	v_add_f32_e32 v26, v26, v27
	v_add_f32_e32 v27, v28, v29
	v_fmac_f32_e32 v32, v34, v34
	v_fmac_f32_e32 v33, v36, v36
	v_add_f32_e32 v28, v30, v31
	v_add_f32_e32 v26, v26, v27
	v_add_f32_e32 v26, v26, v28
	v_add_f32_e32 v27, v32, v33
	v_add_f32_e32 v26, v26, v27
	ds_bpermute_b32 v27, v1, v26
	s_waitcnt lgkmcnt(0)
	v_add_f32_e32 v26, v26, v27
	ds_bpermute_b32 v27, v20, v26
	s_waitcnt lgkmcnt(0)
	v_add_f32_e32 v26, v26, v27
	ds_bpermute_b32 v27, v21, v26
	s_waitcnt lgkmcnt(0)
	v_add_f32_e32 v26, v26, v27
	ds_bpermute_b32 v27, v22, v26
	s_waitcnt lgkmcnt(0)
	v_add_f32_e32 v26, v26, v27
	ds_bpermute_b32 v27, v23, v26
	s_waitcnt lgkmcnt(0)
	v_add_f32_e32 v26, v26, v27
	ds_bpermute_b32 v27, v24, v26
	v_cvt_pk_bf16_f32 v28, v46, v47
	v_cvt_pk_bf16_f32 v29, v48, v49
	v_cvt_pk_bf16_f32 v30, v42, v43
	v_cvt_pk_bf16_f32 v31, v44, v45
	global_store_dwordx2 v25, v[28:29], s[4:5] sc1
	global_store_dwordx2 v25, v[30:31], s[4:5] offset:512 sc1
	v_cvt_pk_bf16_f32 v32, v38, v39
	v_cvt_pk_bf16_f32 v33, v40, v41
	global_store_dwordx2 v25, v[32:33], s[4:5] offset:1024 sc1
	v_cvt_pk_bf16_f32 v46, v34, v35
	v_cvt_pk_bf16_f32 v47, v36, v37
	global_store_dwordx2 v25, v[46:47], s[4:5] offset:1536 sc1
	s_and_saveexec_b64 s[18:19], vcc
	s_waitcnt lgkmcnt(0)
	v_add_f32_e32 v26, v26, v27
	v_min_f32_e32 v26, 0x49742400, v26
	v_fma_f32 v26, v26, s40, 0.5
	v_cvt_u32_f32_e32 v26, v26
	global_store_dword v0, v26, s[12:13]
	s_or_b64 exec, exec, s[18:19]
	s_add_u32 s4, s4, s10
	s_addc_u32 s5, s5, s11
	s_add_u32 s12, s12, s14
	s_addc_u32 s13, s13, s15
	s_waitcnt vmcnt(29)
	v_mul_f32_e32 v26, v63, v63
	v_mul_f32_e32 v27, v65, v65
	v_mul_f32_e32 v28, v59, v59
	v_mul_f32_e32 v29, v61, v61
	v_mul_f32_e32 v30, v55, v55
	v_mul_f32_e32 v31, v57, v57
	v_fmac_f32_e32 v26, v62, v62
	v_fmac_f32_e32 v27, v64, v64
	v_fmac_f32_e32 v28, v58, v58
	v_fmac_f32_e32 v29, v60, v60
	v_mul_f32_e32 v32, v51, v51
	v_mul_f32_e32 v33, v53, v53
	v_fmac_f32_e32 v30, v54, v54
	v_fmac_f32_e32 v31, v56, v56
	v_add_f32_e32 v26, v26, v27
	v_add_f32_e32 v27, v28, v29
	v_fmac_f32_e32 v32, v50, v50
	v_fmac_f32_e32 v33, v52, v52
	v_add_f32_e32 v28, v30, v31
	v_add_f32_e32 v26, v26, v27
	v_add_f32_e32 v26, v26, v28
	v_add_f32_e32 v27, v32, v33
	v_add_f32_e32 v26, v26, v27
	ds_bpermute_b32 v27, v1, v26
	s_waitcnt lgkmcnt(0)
	v_add_f32_e32 v26, v26, v27
	ds_bpermute_b32 v27, v20, v26
	s_waitcnt lgkmcnt(0)
	v_add_f32_e32 v26, v26, v27
	ds_bpermute_b32 v27, v21, v26
	s_waitcnt lgkmcnt(0)
	v_add_f32_e32 v26, v26, v27
	ds_bpermute_b32 v27, v22, v26
	s_waitcnt lgkmcnt(0)
	v_add_f32_e32 v26, v26, v27
	ds_bpermute_b32 v27, v23, v26
	s_waitcnt lgkmcnt(0)
	v_add_f32_e32 v26, v26, v27
	ds_bpermute_b32 v27, v24, v26
	v_cvt_pk_bf16_f32 v28, v62, v63
	v_cvt_pk_bf16_f32 v29, v64, v65
	v_cvt_pk_bf16_f32 v30, v58, v59
	v_cvt_pk_bf16_f32 v31, v60, v61
	global_store_dwordx2 v25, v[28:29], s[4:5] sc1
	global_store_dwordx2 v25, v[30:31], s[4:5] offset:512 sc1
	v_cvt_pk_bf16_f32 v32, v54, v55
	v_cvt_pk_bf16_f32 v33, v56, v57
	global_store_dwordx2 v25, v[32:33], s[4:5] offset:1024 sc1
	v_cvt_pk_bf16_f32 v62, v50, v51
	v_cvt_pk_bf16_f32 v63, v52, v53
	global_store_dwordx2 v25, v[62:63], s[4:5] offset:1536 sc1
	s_and_saveexec_b64 s[18:19], vcc
	s_waitcnt lgkmcnt(0)
	v_add_f32_e32 v26, v26, v27
	v_min_f32_e32 v26, 0x49742400, v26
	v_fma_f32 v26, v26, s40, 0.5
	v_cvt_u32_f32_e32 v26, v26
	global_store_dword v0, v26, s[12:13]
	s_or_b64 exec, exec, s[18:19]
	s_add_u32 s4, s4, s10
	s_addc_u32 s5, s5, s11
	s_add_u32 s12, s12, s14
	s_addc_u32 s13, s13, s15
	s_waitcnt vmcnt(30)
	v_mul_f32_e32 v26, v79, v79
	v_mul_f32_e32 v27, v81, v81
	v_mul_f32_e32 v28, v75, v75
	v_mul_f32_e32 v29, v77, v77
	v_mul_f32_e32 v30, v71, v71
	v_mul_f32_e32 v31, v73, v73
	v_fmac_f32_e32 v26, v78, v78
	v_fmac_f32_e32 v27, v80, v80
	v_fmac_f32_e32 v28, v74, v74
	v_fmac_f32_e32 v29, v76, v76
	v_mul_f32_e32 v32, v67, v67
	v_mul_f32_e32 v33, v69, v69
	v_fmac_f32_e32 v30, v70, v70
	v_fmac_f32_e32 v31, v72, v72
	v_add_f32_e32 v26, v26, v27
	v_add_f32_e32 v27, v28, v29
	v_fmac_f32_e32 v32, v66, v66
	v_fmac_f32_e32 v33, v68, v68
	v_add_f32_e32 v28, v30, v31
	v_add_f32_e32 v26, v26, v27
	v_add_f32_e32 v26, v26, v28
	v_add_f32_e32 v27, v32, v33
	v_add_f32_e32 v26, v26, v27
	ds_bpermute_b32 v27, v1, v26
	s_waitcnt lgkmcnt(0)
	v_add_f32_e32 v26, v26, v27
	ds_bpermute_b32 v27, v20, v26
	s_waitcnt lgkmcnt(0)
	v_add_f32_e32 v26, v26, v27
	ds_bpermute_b32 v27, v21, v26
	s_waitcnt lgkmcnt(0)
	v_add_f32_e32 v26, v26, v27
	ds_bpermute_b32 v27, v22, v26
	s_waitcnt lgkmcnt(0)
	v_add_f32_e32 v26, v26, v27
	ds_bpermute_b32 v27, v23, v26
	s_waitcnt lgkmcnt(0)
	v_add_f32_e32 v26, v26, v27
	ds_bpermute_b32 v27, v24, v26
	v_cvt_pk_bf16_f32 v28, v78, v79
	v_cvt_pk_bf16_f32 v29, v80, v81
	v_cvt_pk_bf16_f32 v30, v74, v75
	v_cvt_pk_bf16_f32 v31, v76, v77
	global_store_dwordx2 v25, v[28:29], s[4:5] sc1
	global_store_dwordx2 v25, v[30:31], s[4:5] offset:512 sc1
	v_cvt_pk_bf16_f32 v32, v70, v71
	v_cvt_pk_bf16_f32 v33, v72, v73
	global_store_dwordx2 v25, v[32:33], s[4:5] offset:1024 sc1
	v_cvt_pk_bf16_f32 v78, v66, v67
	v_cvt_pk_bf16_f32 v79, v68, v69
	global_store_dwordx2 v25, v[78:79], s[4:5] offset:1536 sc1
	s_and_saveexec_b64 s[18:19], vcc
	s_waitcnt lgkmcnt(0)
	v_add_f32_e32 v26, v26, v27
	v_min_f32_e32 v26, 0x49742400, v26
	v_fma_f32 v26, v26, s40, 0.5
	v_cvt_u32_f32_e32 v26, v26
	global_store_dword v0, v26, s[12:13]
	s_or_b64 exec, exec, s[18:19]
	s_add_u32 s4, s4, s10
	s_addc_u32 s5, s5, s11
	s_add_u32 s12, s12, s14
	s_addc_u32 s13, s13, s15
	s_waitcnt vmcnt(31)
	v_mul_f32_e32 v26, v95, v95
	v_mul_f32_e32 v27, v97, v97
	v_mul_f32_e32 v28, v91, v91
	v_mul_f32_e32 v29, v93, v93
	v_mul_f32_e32 v30, v87, v87
	v_mul_f32_e32 v31, v89, v89
	v_fmac_f32_e32 v26, v94, v94
	v_fmac_f32_e32 v27, v96, v96
	v_fmac_f32_e32 v28, v90, v90
	v_fmac_f32_e32 v29, v92, v92
	v_mul_f32_e32 v32, v83, v83
	v_mul_f32_e32 v33, v85, v85
	v_fmac_f32_e32 v30, v86, v86
	v_fmac_f32_e32 v31, v88, v88
	v_add_f32_e32 v26, v26, v27
	v_add_f32_e32 v27, v28, v29
	v_fmac_f32_e32 v32, v82, v82
	v_fmac_f32_e32 v33, v84, v84
	v_add_f32_e32 v28, v30, v31
	v_add_f32_e32 v26, v26, v27
	v_add_f32_e32 v26, v26, v28
	v_add_f32_e32 v27, v32, v33
	v_add_f32_e32 v26, v26, v27
	ds_bpermute_b32 v27, v1, v26
	s_waitcnt lgkmcnt(0)
	v_add_f32_e32 v26, v26, v27
	ds_bpermute_b32 v27, v20, v26
	s_waitcnt lgkmcnt(0)
	v_add_f32_e32 v26, v26, v27
	ds_bpermute_b32 v27, v21, v26
	s_waitcnt lgkmcnt(0)
	v_add_f32_e32 v26, v26, v27
	ds_bpermute_b32 v27, v22, v26
	s_waitcnt lgkmcnt(0)
	v_add_f32_e32 v26, v26, v27
	ds_bpermute_b32 v27, v23, v26
	s_waitcnt lgkmcnt(0)
	v_add_f32_e32 v26, v26, v27
	ds_bpermute_b32 v27, v24, v26
	v_cvt_pk_bf16_f32 v28, v94, v95
	v_cvt_pk_bf16_f32 v29, v96, v97
	v_cvt_pk_bf16_f32 v30, v90, v91
	v_cvt_pk_bf16_f32 v31, v92, v93
	global_store_dwordx2 v25, v[28:29], s[4:5] sc1
	global_store_dwordx2 v25, v[30:31], s[4:5] offset:512 sc1
	v_cvt_pk_bf16_f32 v32, v86, v87
	v_cvt_pk_bf16_f32 v33, v88, v89
	global_store_dwordx2 v25, v[32:33], s[4:5] offset:1024 sc1
	v_cvt_pk_bf16_f32 v94, v82, v83
	v_cvt_pk_bf16_f32 v95, v84, v85
	global_store_dwordx2 v25, v[94:95], s[4:5] offset:1536 sc1
	s_and_saveexec_b64 s[18:19], vcc
	s_waitcnt lgkmcnt(0)
	v_add_f32_e32 v26, v26, v27
	v_min_f32_e32 v26, 0x49742400, v26
	v_fma_f32 v26, v26, s40, 0.5
	v_cvt_u32_f32_e32 v26, v26
	global_store_dword v0, v26, s[12:13]
	s_or_b64 exec, exec, s[18:19]
	s_add_u32 s4, s4, s10
	s_addc_u32 s5, s5, s11
	s_add_u32 s12, s12, s14
	s_addc_u32 s13, s13, s15
	s_waitcnt vmcnt(32)
	v_mul_f32_e32 v26, v111, v111
	v_mul_f32_e32 v27, v113, v113
	v_mul_f32_e32 v28, v107, v107
	v_mul_f32_e32 v29, v109, v109
	v_mul_f32_e32 v30, v103, v103
	v_mul_f32_e32 v31, v105, v105
	v_fmac_f32_e32 v26, v110, v110
	v_fmac_f32_e32 v27, v112, v112
	v_fmac_f32_e32 v28, v106, v106
	v_fmac_f32_e32 v29, v108, v108
	v_mul_f32_e32 v32, v99, v99
	v_mul_f32_e32 v33, v101, v101
	v_fmac_f32_e32 v30, v102, v102
	v_fmac_f32_e32 v31, v104, v104
	v_add_f32_e32 v26, v26, v27
	v_add_f32_e32 v27, v28, v29
	v_fmac_f32_e32 v32, v98, v98
	v_fmac_f32_e32 v33, v100, v100
	v_add_f32_e32 v28, v30, v31
	v_add_f32_e32 v26, v26, v27
	v_add_f32_e32 v26, v26, v28
	v_add_f32_e32 v27, v32, v33
	v_add_f32_e32 v26, v26, v27
	ds_bpermute_b32 v27, v1, v26
	s_waitcnt lgkmcnt(0)
	v_add_f32_e32 v26, v26, v27
	ds_bpermute_b32 v27, v20, v26
	s_waitcnt lgkmcnt(0)
	v_add_f32_e32 v26, v26, v27
	ds_bpermute_b32 v27, v21, v26
	s_waitcnt lgkmcnt(0)
	v_add_f32_e32 v26, v26, v27
	ds_bpermute_b32 v27, v22, v26
	s_waitcnt lgkmcnt(0)
	v_add_f32_e32 v26, v26, v27
	ds_bpermute_b32 v27, v23, v26
	s_waitcnt lgkmcnt(0)
	v_add_f32_e32 v26, v26, v27
	ds_bpermute_b32 v27, v24, v26
	v_cvt_pk_bf16_f32 v28, v110, v111
	v_cvt_pk_bf16_f32 v29, v112, v113
	v_cvt_pk_bf16_f32 v30, v106, v107
	v_cvt_pk_bf16_f32 v31, v108, v109
	global_store_dwordx2 v25, v[28:29], s[4:5] sc1
	global_store_dwordx2 v25, v[30:31], s[4:5] offset:512 sc1
	v_cvt_pk_bf16_f32 v32, v102, v103
	v_cvt_pk_bf16_f32 v33, v104, v105
	global_store_dwordx2 v25, v[32:33], s[4:5] offset:1024 sc1
	v_cvt_pk_bf16_f32 v110, v98, v99
	v_cvt_pk_bf16_f32 v111, v100, v101
	global_store_dwordx2 v25, v[110:111], s[4:5] offset:1536 sc1
	s_and_saveexec_b64 s[18:19], vcc
	s_waitcnt lgkmcnt(0)
	v_add_f32_e32 v26, v26, v27
	v_min_f32_e32 v26, 0x49742400, v26
	v_fma_f32 v26, v26, s40, 0.5
	v_cvt_u32_f32_e32 v26, v26
	global_store_dword v0, v26, s[12:13]
	s_or_b64 exec, exec, s[18:19]
	s_add_u32 s4, s4, s10
	s_addc_u32 s5, s5, s11
	s_add_u32 s12, s12, s14
	s_addc_u32 s13, s13, s15
	s_waitcnt vmcnt(33)
	v_mul_f32_e32 v26, v127, v127
	v_mul_f32_e32 v27, v129, v129
	v_mul_f32_e32 v28, v123, v123
	v_mul_f32_e32 v29, v125, v125
	v_mul_f32_e32 v30, v119, v119
	v_mul_f32_e32 v31, v121, v121
	v_fmac_f32_e32 v26, v126, v126
	v_fmac_f32_e32 v27, v128, v128
	v_fmac_f32_e32 v28, v122, v122
	v_fmac_f32_e32 v29, v124, v124
	v_mul_f32_e32 v32, v115, v115
	v_mul_f32_e32 v33, v117, v117
	v_fmac_f32_e32 v30, v118, v118
	v_fmac_f32_e32 v31, v120, v120
	v_add_f32_e32 v26, v26, v27
	v_add_f32_e32 v27, v28, v29
	v_fmac_f32_e32 v32, v114, v114
	v_fmac_f32_e32 v33, v116, v116
	v_add_f32_e32 v28, v30, v31
	v_add_f32_e32 v26, v26, v27
	v_add_f32_e32 v26, v26, v28
	v_add_f32_e32 v27, v32, v33
	v_add_f32_e32 v26, v26, v27
	ds_bpermute_b32 v27, v1, v26
	s_waitcnt lgkmcnt(0)
	v_add_f32_e32 v26, v26, v27
	ds_bpermute_b32 v27, v20, v26
	s_waitcnt lgkmcnt(0)
	v_add_f32_e32 v26, v26, v27
	ds_bpermute_b32 v27, v21, v26
	s_waitcnt lgkmcnt(0)
	v_add_f32_e32 v26, v26, v27
	ds_bpermute_b32 v27, v22, v26
	s_waitcnt lgkmcnt(0)
	v_add_f32_e32 v26, v26, v27
	ds_bpermute_b32 v27, v23, v26
	s_waitcnt lgkmcnt(0)
	v_add_f32_e32 v26, v26, v27
	ds_bpermute_b32 v27, v24, v26
	v_cvt_pk_bf16_f32 v28, v126, v127
	v_cvt_pk_bf16_f32 v29, v128, v129
	v_cvt_pk_bf16_f32 v30, v122, v123
	v_cvt_pk_bf16_f32 v31, v124, v125
	global_store_dwordx2 v25, v[28:29], s[4:5] sc1
	global_store_dwordx2 v25, v[30:31], s[4:5] offset:512 sc1
	v_cvt_pk_bf16_f32 v32, v118, v119
	v_cvt_pk_bf16_f32 v33, v120, v121
	global_store_dwordx2 v25, v[32:33], s[4:5] offset:1024 sc1
	v_cvt_pk_bf16_f32 v126, v114, v115
	v_cvt_pk_bf16_f32 v127, v116, v117
	global_store_dwordx2 v25, v[126:127], s[4:5] offset:1536 sc1
	s_and_saveexec_b64 s[18:19], vcc
	s_waitcnt lgkmcnt(0)
	v_add_f32_e32 v26, v26, v27
	v_min_f32_e32 v26, 0x49742400, v26
	v_fma_f32 v26, v26, s40, 0.5
	v_cvt_u32_f32_e32 v26, v26
	global_store_dword v0, v26, s[12:13]
	s_or_b64 exec, exec, s[18:19]
	s_add_u32 s4, s4, s10
	s_addc_u32 s5, s5, s11
	s_add_u32 s12, s12, s14
	s_addc_u32 s13, s13, s15
	s_waitcnt vmcnt(34)
	v_mul_f32_e32 v26, v143, v143
	v_mul_f32_e32 v27, v145, v145
	v_mul_f32_e32 v28, v139, v139
	v_mul_f32_e32 v29, v141, v141
	v_mul_f32_e32 v30, v135, v135
	v_mul_f32_e32 v31, v137, v137
	v_fmac_f32_e32 v26, v142, v142
	v_fmac_f32_e32 v27, v144, v144
	v_fmac_f32_e32 v28, v138, v138
	v_fmac_f32_e32 v29, v140, v140
	v_mul_f32_e32 v32, v131, v131
	v_mul_f32_e32 v33, v133, v133
	v_fmac_f32_e32 v30, v134, v134
	v_fmac_f32_e32 v31, v136, v136
	v_add_f32_e32 v26, v26, v27
	v_add_f32_e32 v27, v28, v29
	v_fmac_f32_e32 v32, v130, v130
	v_fmac_f32_e32 v33, v132, v132
	v_add_f32_e32 v28, v30, v31
	v_add_f32_e32 v26, v26, v27
	v_add_f32_e32 v26, v26, v28
	v_add_f32_e32 v27, v32, v33
	v_add_f32_e32 v26, v26, v27
	ds_bpermute_b32 v27, v1, v26
	s_waitcnt lgkmcnt(0)
	v_add_f32_e32 v26, v26, v27
	ds_bpermute_b32 v27, v20, v26
	s_waitcnt lgkmcnt(0)
	v_add_f32_e32 v26, v26, v27
	ds_bpermute_b32 v27, v21, v26
	s_waitcnt lgkmcnt(0)
	v_add_f32_e32 v26, v26, v27
	ds_bpermute_b32 v27, v22, v26
	s_waitcnt lgkmcnt(0)
	v_add_f32_e32 v26, v26, v27
	ds_bpermute_b32 v27, v23, v26
	s_waitcnt lgkmcnt(0)
	v_add_f32_e32 v26, v26, v27
	ds_bpermute_b32 v27, v24, v26
	v_cvt_pk_bf16_f32 v28, v142, v143
	v_cvt_pk_bf16_f32 v29, v144, v145
	v_cvt_pk_bf16_f32 v30, v138, v139
	v_cvt_pk_bf16_f32 v31, v140, v141
	global_store_dwordx2 v25, v[28:29], s[4:5] sc1
	global_store_dwordx2 v25, v[30:31], s[4:5] offset:512 sc1
	v_cvt_pk_bf16_f32 v32, v134, v135
	v_cvt_pk_bf16_f32 v33, v136, v137
	global_store_dwordx2 v25, v[32:33], s[4:5] offset:1024 sc1
	v_cvt_pk_bf16_f32 v142, v130, v131
	v_cvt_pk_bf16_f32 v143, v132, v133
	global_store_dwordx2 v25, v[142:143], s[4:5] offset:1536 sc1
	s_and_saveexec_b64 s[18:19], vcc
	s_waitcnt lgkmcnt(0)
	v_add_f32_e32 v26, v26, v27
	v_min_f32_e32 v26, 0x49742400, v26
	v_fma_f32 v26, v26, s40, 0.5
	v_cvt_u32_f32_e32 v26, v26
	global_store_dword v0, v26, s[12:13]
	s_or_b64 exec, exec, s[18:19]
	s_add_u32 s4, s4, s10
	s_addc_u32 s5, s5, s11
	s_add_u32 s12, s12, s14
	s_addc_u32 s13, s13, s15
	s_waitcnt vmcnt(35)
	v_mul_f32_e32 v26, v159, v159
	v_mul_f32_e32 v27, v161, v161
	v_mul_f32_e32 v28, v155, v155
	v_mul_f32_e32 v29, v157, v157
	v_mul_f32_e32 v30, v151, v151
	v_mul_f32_e32 v31, v153, v153
	v_fmac_f32_e32 v26, v158, v158
	v_fmac_f32_e32 v27, v160, v160
	v_fmac_f32_e32 v28, v154, v154
	v_fmac_f32_e32 v29, v156, v156
	v_mul_f32_e32 v32, v147, v147
	v_mul_f32_e32 v33, v149, v149
	v_fmac_f32_e32 v30, v150, v150
	v_fmac_f32_e32 v31, v152, v152
	v_add_f32_e32 v26, v26, v27
	v_add_f32_e32 v27, v28, v29
	v_fmac_f32_e32 v32, v146, v146
	v_fmac_f32_e32 v33, v148, v148
	v_add_f32_e32 v28, v30, v31
	v_add_f32_e32 v26, v26, v27
	v_add_f32_e32 v26, v26, v28
	v_add_f32_e32 v27, v32, v33
	v_add_f32_e32 v26, v26, v27
	ds_bpermute_b32 v27, v1, v26
	s_waitcnt lgkmcnt(0)
	v_add_f32_e32 v26, v26, v27
	ds_bpermute_b32 v27, v20, v26
	s_waitcnt lgkmcnt(0)
	v_add_f32_e32 v26, v26, v27
	ds_bpermute_b32 v27, v21, v26
	s_waitcnt lgkmcnt(0)
	v_add_f32_e32 v26, v26, v27
	ds_bpermute_b32 v27, v22, v26
	s_waitcnt lgkmcnt(0)
	v_add_f32_e32 v26, v26, v27
	ds_bpermute_b32 v27, v23, v26
	s_waitcnt lgkmcnt(0)
	v_add_f32_e32 v26, v26, v27
	ds_bpermute_b32 v27, v24, v26
	v_cvt_pk_bf16_f32 v28, v158, v159
	v_cvt_pk_bf16_f32 v29, v160, v161
	v_cvt_pk_bf16_f32 v30, v154, v155
	v_cvt_pk_bf16_f32 v31, v156, v157
	global_store_dwordx2 v25, v[28:29], s[4:5] sc1
	global_store_dwordx2 v25, v[30:31], s[4:5] offset:512 sc1
	v_cvt_pk_bf16_f32 v32, v150, v151
	v_cvt_pk_bf16_f32 v33, v152, v153
	global_store_dwordx2 v25, v[32:33], s[4:5] offset:1024 sc1
	v_cvt_pk_bf16_f32 v158, v146, v147
	v_cvt_pk_bf16_f32 v159, v148, v149
	global_store_dwordx2 v25, v[158:159], s[4:5] offset:1536 sc1
	s_and_saveexec_b64 s[18:19], vcc
	s_waitcnt lgkmcnt(0)
	v_add_f32_e32 v26, v26, v27
	v_min_f32_e32 v26, 0x49742400, v26
	v_fma_f32 v26, v26, s40, 0.5
	v_cvt_u32_f32_e32 v26, v26
	global_store_dword v0, v26, s[12:13]
	s_or_b64 exec, exec, s[18:19]
	s_branch .LBB0_676
